# hand-written grid barrier body: L1 invalidate issued at arrival, monotonic per-XCD counter plus one top counter polled by all blocks (11 in-loop instances)
# speedup vs baseline: 1.2527x; 1.0229x over previous
_Z2mk1Pii:
	s_load_dwordx4 s[44:47], s[0:1], 0x190
	s_add_u32 s4, s0, 0x198
	s_addc_u32 s5, s1, 0
	v_writelane_b32 v164, s2, 0
	v_writelane_b32 v162, 0, 60
	s_waitcnt lgkmcnt(0)
	s_cmp_lt_i32 s45, 0
	s_cbranch_scc1 .LBB0_2
	v_and_b32_e32 v128, 0x3ff, v0
	s_load_dword s33, s[0:1], 0x1a0
	s_cbranch_execz .LBB0_3
	s_branch .LBB0_14

.LBB0_197:
	s_mul_i32 s2, s34, 12
	v_readlane_b32 s20, v162, 12
	s_or_b32 s35, s2, 3
	v_readlane_b32 s21, v162, 13
	s_cmp_ge_u32 s35, s21
	v_readlane_b32 s22, v162, 14
	v_readlane_b32 s23, v162, 15
	s_cbranch_scc1 .LBB0_247
	s_waitcnt vmcnt(0)
	v_readlane_b32 s4, v163, 17
	v_readlane_b32 s5, v163, 18
	s_barrier
	s_and_saveexec_b64 s[2:3], s[4:5]
	s_cbranch_execz .LBB0_246
	s_waitcnt vmcnt(0) lgkmcnt(0)
	buffer_inv sc1
	ds_read_b32 v2, v117 offset:53248
	ds_read_b32 v3, v117 offset:53252
	v_readlane_b32 s4, v163, 62
	v_readlane_b32 s5, v163, 63
	v_readlane_b32 s36, v162, 60
	s_nop 1
	s_add_u32 s36, s36, 1
	s_nop 2
	v_writelane_b32 v162, s36, 60
	global_atomic_add v0, v117, v129, s[4:5] offset:64 sc0
	s_waitcnt lgkmcnt(0)
	v_mul_lo_u32 v2, v2, s36
	v_mul_lo_u32 v3, v3, s36
	v_readlane_b32 s4, v162, 2
	v_readlane_b32 s5, v162, 3
	s_waitcnt vmcnt(0)
	v_add_u32_e32 v0, 1, v0
	s_nop 0
	v_cmp_eq_u32_e32 vcc, v0, v2
	s_nop 3
	s_cbranch_vccz .Lxb0_poll
	buffer_wbl2 sc1
	s_waitcnt vmcnt(0)
	global_atomic_add v117, v129, s[4:5] offset:64
.Lxb0_poll:
	s_mov_b32 s20, 0
.Lxb0_spin:
	global_load_dword v0, v117, s[4:5] offset:64 sc1
	s_waitcnt vmcnt(0)
	v_cmp_ge_u32_e32 vcc, v0, v3
	s_cbranch_vccnz .Lxb0_done
	s_sleep 1
	s_add_u32 s20, s20, 1
	s_cmp_lt_u32 s20, 0x400000
	s_cbranch_scc1 .Lxb0_spin
.Lxb0_done:
.LBB0_246:
	s_or_b64 exec, exec, s[2:3]
	s_waitcnt lgkmcnt(0)
	s_barrier

.LBB0_267:
	s_mul_i32 s2, s34, 12
	v_readlane_b32 s20, v162, 12
	s_add_i32 s35, s2, 4
	v_readlane_b32 s21, v162, 13
	s_cmp_ge_i32 s35, s21
	v_readlane_b32 s22, v162, 14
	v_readlane_b32 s23, v162, 15
	s_cbranch_scc1 .LBB0_317
	s_waitcnt vmcnt(0)
	v_readlane_b32 s4, v163, 17
	v_readlane_b32 s5, v163, 18
	s_barrier
	s_and_saveexec_b64 s[2:3], s[4:5]
	s_cbranch_execz .LBB0_316
	s_waitcnt vmcnt(0) lgkmcnt(0)
	buffer_inv sc1
	ds_read_b32 v2, v117 offset:53248
	ds_read_b32 v3, v117 offset:53252
	v_readlane_b32 s4, v163, 62
	v_readlane_b32 s5, v163, 63
	v_readlane_b32 s36, v162, 60
	s_nop 1
	s_add_u32 s36, s36, 1
	s_nop 2
	v_writelane_b32 v162, s36, 60
	global_atomic_add v0, v117, v129, s[4:5] offset:64 sc0
	s_waitcnt lgkmcnt(0)
	v_mul_lo_u32 v2, v2, s36
	v_mul_lo_u32 v3, v3, s36
	v_readlane_b32 s4, v162, 2
	v_readlane_b32 s5, v162, 3
	s_waitcnt vmcnt(0)
	v_add_u32_e32 v0, 1, v0
	s_nop 0
	v_cmp_eq_u32_e32 vcc, v0, v2
	s_nop 3
	s_cbranch_vccz .Lxb1_poll
	buffer_wbl2 sc1
	s_waitcnt vmcnt(0)
	global_atomic_add v117, v129, s[4:5] offset:64

.LBB0_323:
	s_or_b64 exec, exec, s[2:3]
	s_mul_i32 s2, s34, 12
	v_readlane_b32 s20, v162, 12
	s_add_i32 s35, s2, 5
	v_readlane_b32 s21, v162, 13
	s_cmp_ge_i32 s35, s21
	v_readlane_b32 s22, v162, 14
	v_readlane_b32 s23, v162, 15
	s_cbranch_scc1 .LBB0_373
	s_waitcnt vmcnt(0)
	v_readlane_b32 s4, v163, 17
	v_readlane_b32 s5, v163, 18
	s_barrier
	s_and_saveexec_b64 s[2:3], s[4:5]
	s_cbranch_execz .LBB0_372
	s_waitcnt vmcnt(0) lgkmcnt(0)
	buffer_inv sc1
	ds_read_b32 v2, v117 offset:53248
	ds_read_b32 v3, v117 offset:53252
	v_readlane_b32 s4, v163, 62
	v_readlane_b32 s5, v163, 63
	v_readlane_b32 s36, v162, 60
	s_nop 1
	s_add_u32 s36, s36, 1
	s_nop 2
	v_writelane_b32 v162, s36, 60
	global_atomic_add v0, v117, v129, s[4:5] offset:64 sc0
	s_waitcnt lgkmcnt(0)
	v_mul_lo_u32 v2, v2, s36
	v_mul_lo_u32 v3, v3, s36
	v_readlane_b32 s4, v162, 2
	v_readlane_b32 s5, v162, 3
	s_waitcnt vmcnt(0)
	v_add_u32_e32 v0, 1, v0
	s_nop 0
	v_cmp_eq_u32_e32 vcc, v0, v2
	s_nop 3
	s_cbranch_vccz .Lxb2_poll
	buffer_wbl2 sc1
	s_waitcnt vmcnt(0)
	global_atomic_add v117, v129, s[4:5] offset:64

.LBB0_471:
	s_mul_i32 s2, s34, 12
	v_readlane_b32 s20, v162, 12
	s_add_i32 s35, s2, 6
	v_readlane_b32 s21, v162, 13
	s_cmp_ge_i32 s35, s21
	v_readlane_b32 s22, v162, 14
	v_readlane_b32 s23, v162, 15
	s_cbranch_scc1 .LBB0_521
	s_waitcnt vmcnt(0)
	v_readlane_b32 s4, v163, 17
	v_readlane_b32 s5, v163, 18
	s_barrier
	s_and_saveexec_b64 s[2:3], s[4:5]
	s_cbranch_execz .LBB0_520
	s_waitcnt vmcnt(0) lgkmcnt(0)
	buffer_inv sc1
	ds_read_b32 v2, v117 offset:53248
	ds_read_b32 v3, v117 offset:53252
	v_readlane_b32 s4, v163, 62
	v_readlane_b32 s5, v163, 63
	v_readlane_b32 s36, v162, 60
	s_nop 1
	s_add_u32 s36, s36, 1
	s_nop 2
	v_writelane_b32 v162, s36, 60
	global_atomic_add v0, v117, v129, s[4:5] offset:64 sc0
	s_waitcnt lgkmcnt(0)
	v_mul_lo_u32 v2, v2, s36
	v_mul_lo_u32 v3, v3, s36
	v_readlane_b32 s4, v162, 2
	v_readlane_b32 s5, v162, 3
	s_waitcnt vmcnt(0)
	v_add_u32_e32 v0, 1, v0
	s_nop 0
	v_cmp_eq_u32_e32 vcc, v0, v2
	s_nop 3
	s_cbranch_vccz .Lxb3_poll
	buffer_wbl2 sc1
	s_waitcnt vmcnt(0)
	global_atomic_add v117, v129, s[4:5] offset:64

.LBB0_547:
	s_or_b64 exec, exec, s[2:3]
	v_readlane_b32 s2, v162, 36
	v_readlane_b32 s20, v162, 12
	s_add_i32 s35, s2, 7
	v_readlane_b32 s21, v162, 13
	s_cmp_ge_i32 s35, s21
	v_readlane_b32 s22, v162, 14
	v_readlane_b32 s23, v162, 15
	s_cbranch_scc1 .LBB0_597
	s_waitcnt vmcnt(0)
	v_readlane_b32 s4, v163, 17
	v_readlane_b32 s5, v163, 18
	s_barrier
	s_and_saveexec_b64 s[2:3], s[4:5]
	s_cbranch_execz .LBB0_596
	s_waitcnt vmcnt(0) lgkmcnt(0)
	buffer_inv sc1
	ds_read_b32 v2, v117 offset:53248
	ds_read_b32 v3, v117 offset:53252
	v_readlane_b32 s4, v163, 62
	v_readlane_b32 s5, v163, 63
	v_readlane_b32 s36, v162, 60
	s_nop 1
	s_add_u32 s36, s36, 1
	s_nop 2
	v_writelane_b32 v162, s36, 60
	global_atomic_add v0, v117, v129, s[4:5] offset:64 sc0
	s_waitcnt lgkmcnt(0)
	v_mul_lo_u32 v2, v2, s36
	v_mul_lo_u32 v3, v3, s36
	v_readlane_b32 s4, v162, 2
	v_readlane_b32 s5, v162, 3
	s_waitcnt vmcnt(0)
	v_add_u32_e32 v0, 1, v0
	s_nop 0
	v_cmp_eq_u32_e32 vcc, v0, v2
	s_nop 3
	s_cbranch_vccz .Lxb4_poll
	buffer_wbl2 sc1
	s_waitcnt vmcnt(0)
	global_atomic_add v117, v129, s[4:5] offset:64

.LBB0_749:
	v_readlane_b32 s2, v162, 36
	v_readlane_b32 s20, v162, 12
	s_add_i32 s35, s2, 8
	v_readlane_b32 s21, v162, 13
	s_cmp_ge_i32 s35, s21
	v_readlane_b32 s22, v162, 14
	v_readlane_b32 s23, v162, 15
	s_cbranch_scc1 .LBB0_799
	s_waitcnt vmcnt(0)
	v_readlane_b32 s4, v163, 17
	v_readlane_b32 s5, v163, 18
	s_barrier
	s_and_saveexec_b64 s[2:3], s[4:5]
	s_cbranch_execz .LBB0_798
	s_waitcnt vmcnt(0) lgkmcnt(0)
	buffer_inv sc1
	ds_read_b32 v2, v117 offset:53248
	ds_read_b32 v3, v117 offset:53252
	v_readlane_b32 s4, v163, 62
	v_readlane_b32 s5, v163, 63
	v_readlane_b32 s36, v162, 60
	s_nop 1
	s_add_u32 s36, s36, 1
	s_nop 2
	v_writelane_b32 v162, s36, 60
	global_atomic_add v0, v117, v129, s[4:5] offset:64 sc0
	s_waitcnt lgkmcnt(0)
	v_mul_lo_u32 v2, v2, s36
	v_mul_lo_u32 v3, v3, s36
	v_readlane_b32 s4, v162, 2
	v_readlane_b32 s5, v162, 3
	s_waitcnt vmcnt(0)
	v_add_u32_e32 v0, 1, v0
	s_nop 0
	v_cmp_eq_u32_e32 vcc, v0, v2
	s_nop 3
	s_cbranch_vccz .Lxb5_poll
	buffer_wbl2 sc1
	s_waitcnt vmcnt(0)
	global_atomic_add v117, v129, s[4:5] offset:64

.LBB0_807:
	s_or_b64 exec, exec, s[2:3]
	v_readlane_b32 s2, v162, 36
	v_readlane_b32 s20, v162, 12
	s_add_i32 s35, s2, 9
	v_readlane_b32 s21, v162, 13
	s_cmp_ge_i32 s35, s21
	v_readlane_b32 s22, v162, 14
	v_readlane_b32 s23, v162, 15
	s_cbranch_scc1 .LBB0_857
	s_waitcnt vmcnt(0)
	v_readlane_b32 s4, v163, 17
	v_readlane_b32 s5, v163, 18
	s_barrier
	s_and_saveexec_b64 s[2:3], s[4:5]
	s_cbranch_execz .LBB0_856
	s_waitcnt vmcnt(0) lgkmcnt(0)
	buffer_inv sc1
	ds_read_b32 v2, v117 offset:53248
	ds_read_b32 v3, v117 offset:53252
	v_readlane_b32 s4, v163, 62
	v_readlane_b32 s5, v163, 63
	v_readlane_b32 s36, v162, 60
	s_nop 1
	s_add_u32 s36, s36, 1
	s_nop 2
	v_writelane_b32 v162, s36, 60
	global_atomic_add v0, v117, v129, s[4:5] offset:64 sc0
	s_waitcnt lgkmcnt(0)
	v_mul_lo_u32 v2, v2, s36
	v_mul_lo_u32 v3, v3, s36
	v_readlane_b32 s4, v162, 2
	v_readlane_b32 s5, v162, 3
	s_waitcnt vmcnt(0)
	v_add_u32_e32 v0, 1, v0
	s_nop 0
	v_cmp_eq_u32_e32 vcc, v0, v2
	s_nop 3
	s_cbranch_vccz .Lxb6_poll
	buffer_wbl2 sc1
	s_waitcnt vmcnt(0)
	global_atomic_add v117, v129, s[4:5] offset:64

.LBB0_877:
	v_readlane_b32 s2, v162, 36
	v_readlane_b32 s20, v162, 12
	s_add_i32 s35, s2, 10
	v_readlane_b32 s21, v162, 13
	s_cmp_ge_i32 s35, s21
	v_readlane_b32 s22, v162, 14
	v_readlane_b32 s23, v162, 15
	s_cbranch_scc1 .LBB0_927
	s_waitcnt vmcnt(0)
	v_readlane_b32 s4, v163, 17
	v_readlane_b32 s5, v163, 18
	s_barrier
	s_and_saveexec_b64 s[2:3], s[4:5]
	s_cbranch_execz .LBB0_926
	s_waitcnt vmcnt(0) lgkmcnt(0)
	buffer_inv sc1
	ds_read_b32 v2, v117 offset:53248
	ds_read_b32 v3, v117 offset:53252
	v_readlane_b32 s4, v163, 62
	v_readlane_b32 s5, v163, 63
	v_readlane_b32 s36, v162, 60
	s_nop 1
	s_add_u32 s36, s36, 1
	s_nop 2
	v_writelane_b32 v162, s36, 60
	global_atomic_add v0, v117, v129, s[4:5] offset:64 sc0
	s_waitcnt lgkmcnt(0)
	v_mul_lo_u32 v2, v2, s36
	v_mul_lo_u32 v3, v3, s36
	v_readlane_b32 s4, v162, 2
	v_readlane_b32 s5, v162, 3
	s_waitcnt vmcnt(0)
	v_add_u32_e32 v0, 1, v0
	s_nop 0
	v_cmp_eq_u32_e32 vcc, v0, v2
	s_nop 3
	s_cbranch_vccz .Lxb7_poll
	buffer_wbl2 sc1
	s_waitcnt vmcnt(0)
	global_atomic_add v117, v129, s[4:5] offset:64

.LBB0_933:
	s_or_b64 exec, exec, s[2:3]
	v_readlane_b32 s2, v162, 36
	v_readlane_b32 s20, v162, 12
	s_add_i32 s35, s2, 11
	v_readlane_b32 s21, v162, 13
	s_cmp_ge_i32 s35, s21
	v_readlane_b32 s22, v162, 14
	v_readlane_b32 s23, v162, 15
	s_cbranch_scc1 .LBB0_983
	s_waitcnt vmcnt(0)
	v_readlane_b32 s4, v163, 17
	v_readlane_b32 s5, v163, 18
	s_barrier
	s_and_saveexec_b64 s[2:3], s[4:5]
	s_cbranch_execz .LBB0_982
	s_waitcnt vmcnt(0) lgkmcnt(0)
	buffer_inv sc1
	ds_read_b32 v2, v117 offset:53248
	ds_read_b32 v3, v117 offset:53252
	v_readlane_b32 s4, v163, 62
	v_readlane_b32 s5, v163, 63
	v_readlane_b32 s36, v162, 60
	s_nop 1
	s_add_u32 s36, s36, 1
	s_nop 2
	v_writelane_b32 v162, s36, 60
	global_atomic_add v0, v117, v129, s[4:5] offset:64 sc0
	s_waitcnt lgkmcnt(0)
	v_mul_lo_u32 v2, v2, s36
	v_mul_lo_u32 v3, v3, s36
	v_readlane_b32 s4, v162, 2
	v_readlane_b32 s5, v162, 3
	s_waitcnt vmcnt(0)
	v_add_u32_e32 v0, 1, v0
	s_nop 0
	v_cmp_eq_u32_e32 vcc, v0, v2
	s_nop 3
	s_cbranch_vccz .Lxb8_poll
	buffer_wbl2 sc1
	s_waitcnt vmcnt(0)
	global_atomic_add v117, v129, s[4:5] offset:64

.LBB0_991:
	v_readlane_b32 s2, v162, 36
	v_readlane_b32 s20, v162, 12
	s_add_i32 s35, s2, 12
	v_readlane_b32 s21, v162, 13
	s_cmp_ge_i32 s35, s21
	v_readlane_b32 s22, v162, 14
	v_readlane_b32 s23, v162, 15
	s_cbranch_scc1 .LBB0_1041
	s_waitcnt vmcnt(0)
	v_readlane_b32 s4, v163, 17
	v_readlane_b32 s5, v163, 18
	s_barrier
	s_and_saveexec_b64 s[2:3], s[4:5]
	s_cbranch_execz .LBB0_1040
	s_waitcnt vmcnt(0) lgkmcnt(0)
	buffer_inv sc1
	ds_read_b32 v2, v117 offset:53248
	ds_read_b32 v3, v117 offset:53252
	v_readlane_b32 s4, v163, 62
	v_readlane_b32 s5, v163, 63
	v_readlane_b32 s36, v162, 60
	s_nop 1
	s_add_u32 s36, s36, 1
	s_nop 2
	v_writelane_b32 v162, s36, 60
	global_atomic_add v0, v117, v129, s[4:5] offset:64 sc0
	s_waitcnt lgkmcnt(0)
	v_mul_lo_u32 v2, v2, s36
	v_mul_lo_u32 v3, v3, s36
	v_readlane_b32 s4, v162, 2
	v_readlane_b32 s5, v162, 3
	s_waitcnt vmcnt(0)
	v_add_u32_e32 v0, 1, v0
	s_nop 0
	v_cmp_eq_u32_e32 vcc, v0, v2
	s_nop 3
	s_cbranch_vccz .Lxb9_poll
	buffer_wbl2 sc1
	s_waitcnt vmcnt(0)
	global_atomic_add v117, v129, s[4:5] offset:64

.LBB0_1061:
	v_readlane_b32 s2, v162, 36
	v_readlane_b32 s20, v162, 12
	s_add_i32 s35, s2, 13
	v_readlane_b32 s21, v162, 13
	s_cmp_ge_i32 s35, s21
	v_readlane_b32 s22, v162, 14
	v_readlane_b32 s23, v162, 15
	s_cbranch_scc1 .LBB0_1111
	s_waitcnt vmcnt(0)
	v_readlane_b32 s4, v163, 17
	v_readlane_b32 s5, v163, 18
	s_barrier
	s_and_saveexec_b64 s[2:3], s[4:5]
	s_cbranch_execz .LBB0_1110
	s_waitcnt vmcnt(0) lgkmcnt(0)
	buffer_inv sc1
	ds_read_b32 v2, v117 offset:53248
	ds_read_b32 v3, v117 offset:53252
	v_readlane_b32 s4, v163, 62
	v_readlane_b32 s5, v163, 63
	v_readlane_b32 s36, v162, 60
	s_nop 1
	s_add_u32 s36, s36, 1
	s_nop 2
	v_writelane_b32 v162, s36, 60
	global_atomic_add v0, v117, v129, s[4:5] offset:64 sc0
	s_waitcnt lgkmcnt(0)
	v_mul_lo_u32 v2, v2, s36
	v_mul_lo_u32 v3, v3, s36
	v_readlane_b32 s4, v162, 2
	v_readlane_b32 s5, v162, 3
	s_waitcnt vmcnt(0)
	v_add_u32_e32 v0, 1, v0
	s_nop 0
	v_cmp_eq_u32_e32 vcc, v0, v2
	s_nop 3
	s_cbranch_vccz .Lxb10_poll
	buffer_wbl2 sc1
	s_waitcnt vmcnt(0)
	global_atomic_add v117, v129, s[4:5] offset:64
